# GLA-C chunk-state prefix remainder loop software-pipelined two deep (next chunk's 8 loads issued into a second register set before waiting on the current chunk)
# speedup vs baseline: 1.0059x; 1.0059x over previous
; __device__ void gla_passC_item(const Params& p, int l, int item, unsigned char* ldsraw) {
;     ...
;   {
;     const float* gS = (const float*)(p.ws + WS_GLAS) + (size_t)(bh * 64) * 2048;
;     const float* gD = (const float*)(p.ws + WS_GLAD) + (size_t)(bh * 64) * 32;
;     float a[4] = {0.f, 0.f, 0.f, 0.f};
; #pragma unroll 8
;     for (int cc = 0; cc < c; ++cc) {
; #pragma unroll
;       for (int i = 0; i < 4; ++i) {
;         const int e = tid + NT * i;
;         a[i] = a[i] * gD[cc * 32 + (e >> 6)] + gS[(size_t)cc * 2048 + e];
;       }
;     }
; #pragma unroll
;     for (int i = 0; i < 4; ++i) S0[tid + NT * i] = a[i];
;   }
.LBB0_487:
	v_add_u32_e32 v14, s1, v12
	v_add_u32_e32 v16, s1, v5
	v_add_u32_e32 v22, s1, v3
	v_add_u32_e32 v24, s1, v0
	v_add_co_u32_e32 v26, vcc, s40, v18
	v_ashrrev_i32_e32 v15, 31, v14
	v_ashrrev_i32_e32 v17, 31, v16
	v_addc_co_u32_e32 v27, vcc, 0, v19, vcc
	v_ashrrev_i32_e32 v23, 31, v22
	v_ashrrev_i32_e32 v25, 31, v24
	v_lshl_add_u64 v[14:15], v[14:15], 2, s[6:7]
	v_lshl_add_u64 v[16:17], v[16:17], 2, s[6:7]
	global_load_dword v21, v[18:19], off
	global_load_dword v20, v[18:19], off offset:2048
	global_load_dword v29, v[26:27], off
	global_load_dword v28, v[26:27], off offset:2048
	v_lshl_add_u64 v[22:23], v[22:23], 2, s[6:7]
	v_lshl_add_u64 v[24:25], v[24:25], 2, s[6:7]
	global_load_dword v15, v[14:15], off
	s_nop 0
	global_load_dword v14, v[16:17], off
	s_nop 0
	global_load_dword v17, v[22:23], off
	global_load_dword v16, v[24:25], off
	s_add_i32 s1, s1, 32
	s_mov_b64 s[10:11], 0x2000
	v_lshl_add_u64 v[18:19], v[18:19], 0, s[10:11]
	s_cmp_lg_u32 s0, s1
	s_cbranch_scc0 .Lgc_drainP
.Lgc_loop:
	v_add_u32_e32 v232, s1, v12
	v_add_u32_e32 v234, s1, v5
	v_add_u32_e32 v224, s1, v3
	v_add_u32_e32 v226, s1, v0
	v_add_co_u32_e32 v222, vcc, s40, v18
	v_ashrrev_i32_e32 v233, 31, v232
	v_ashrrev_i32_e32 v235, 31, v234
	v_addc_co_u32_e32 v223, vcc, 0, v19, vcc
	v_ashrrev_i32_e32 v225, 31, v224
	v_ashrrev_i32_e32 v227, 31, v226
	v_lshl_add_u64 v[232:233], v[232:233], 2, s[6:7]
	v_lshl_add_u64 v[234:235], v[234:235], 2, s[6:7]
	global_load_dword v229, v[18:19], off
	global_load_dword v228, v[18:19], off offset:2048
	global_load_dword v231, v[222:223], off
	global_load_dword v230, v[222:223], off offset:2048
	v_lshl_add_u64 v[224:225], v[224:225], 2, s[6:7]
	v_lshl_add_u64 v[226:227], v[226:227], 2, s[6:7]
	global_load_dword v233, v[232:233], off
	s_nop 0
	global_load_dword v232, v[234:235], off
	s_nop 0
	global_load_dword v235, v[224:225], off
	global_load_dword v234, v[226:227], off
	s_add_i32 s1, s1, 32
	s_mov_b64 s[10:11], 0x2000
	v_lshl_add_u64 v[18:19], v[18:19], 0, s[10:11]
	s_waitcnt vmcnt(10)
	v_pk_fma_f32 v[10:11], v[10:11], v[14:15], v[20:21]
	s_waitcnt vmcnt(8)
	v_pk_fma_f32 v[8:9], v[8:9], v[16:17], v[28:29]
	s_cmp_lg_u32 s0, s1
	s_cbranch_scc0 .Lgc_drainQ
	v_add_u32_e32 v14, s1, v12
	v_add_u32_e32 v16, s1, v5
	v_add_u32_e32 v22, s1, v3
	v_add_u32_e32 v24, s1, v0
	v_add_co_u32_e32 v26, vcc, s40, v18
	v_ashrrev_i32_e32 v15, 31, v14
	v_ashrrev_i32_e32 v17, 31, v16
	v_addc_co_u32_e32 v27, vcc, 0, v19, vcc
	v_ashrrev_i32_e32 v23, 31, v22
	v_ashrrev_i32_e32 v25, 31, v24
	v_lshl_add_u64 v[14:15], v[14:15], 2, s[6:7]
	v_lshl_add_u64 v[16:17], v[16:17], 2, s[6:7]
	global_load_dword v21, v[18:19], off
	global_load_dword v20, v[18:19], off offset:2048
	global_load_dword v29, v[26:27], off
	global_load_dword v28, v[26:27], off offset:2048
	v_lshl_add_u64 v[22:23], v[22:23], 2, s[6:7]
	v_lshl_add_u64 v[24:25], v[24:25], 2, s[6:7]
	global_load_dword v15, v[14:15], off
	s_nop 0
	global_load_dword v14, v[16:17], off
	s_nop 0
	global_load_dword v17, v[22:23], off
	global_load_dword v16, v[24:25], off
	s_add_i32 s1, s1, 32
	s_mov_b64 s[10:11], 0x2000
	v_lshl_add_u64 v[18:19], v[18:19], 0, s[10:11]
	s_waitcnt vmcnt(10)
	v_pk_fma_f32 v[10:11], v[10:11], v[232:233], v[228:229]
	s_waitcnt vmcnt(8)
	v_pk_fma_f32 v[8:9], v[8:9], v[234:235], v[230:231]
	s_cmp_lg_u32 s0, s1
	s_cbranch_scc1 .Lgc_loop
.Lgc_drainP:
	s_waitcnt vmcnt(2)
	v_pk_fma_f32 v[10:11], v[10:11], v[14:15], v[20:21]
	s_waitcnt vmcnt(0)
	v_pk_fma_f32 v[8:9], v[8:9], v[16:17], v[28:29]
	s_branch .LBB0_488
.Lgc_drainQ:
	s_waitcnt vmcnt(2)
	v_pk_fma_f32 v[10:11], v[10:11], v[232:233], v[228:229]
	s_waitcnt vmcnt(0)
	v_pk_fma_f32 v[8:9], v[8:9], v[234:235], v[230:231]
